# v43 + FoX tile loop: next-tile K/V/F loads interleaved into the QK MFMA cluster (MFMA/VMEM interleave), separate paths for last tile and inactive wave
# speedup vs baseline: 1.0033x; 1.0033x over previous
; #define MFMA(a, b, c) __builtin_amdgcn_mfma_f32_32x32x16_bf16((a), (b), (c), 0, 0, 0)
; template <int DK, int MODE> ...
;     ...
;   for (int it = 0; it < nit; ++it) {
;     const int jt = ASC ? start + it : ntiles - 1 - it;
;     const int cur = it & 1;
;     const bool more = it + 1 < nit;
;     if (more) gload(ASC ? jt + 1 : jt - 1);
;     const int key0 = jt * 64;
;     const bool active = !CAUSAL || (key0 <= tq0 + 31);
;     if (active) {
;       f32x16 s0, s1;
;       const bf16_t* kb = sK + cur * 64 * LDK + l32 * LDK + h * 8;
;       bf16x8 kf0[NKS], kf1[NKS];
; #pragma unroll
;       for (int ks = 0; ks < NKS; ++ks) { kf0[ks] = *(const bf16x8*)(kb + ks * 16); kf1[ks] = *(const bf16x8*)(kb + 32 * LDK + ks * 16); }
;       if (MODE == 1) {
;         const float* fb = sF + cur * 64 + 4 * h;
; #pragma unroll
;         for (int g = 0; g < 4; ++g) {
;           const f32x4 f0 = *(const f32x4*)(fb + 8 * g), f1 = *(const f32x4*)(fb + 32 + 8 * g);
;           s0[4 * g] = f0.x; s0[4 * g + 1] = f0.y; s0[4 * g + 2] = f0.z; s0[4 * g + 3] = f0.w;
;           s1[4 * g] = f1.x; s1[4 * g + 1] = f1.y; s1[4 * g + 2] = f1.z; s1[4 * g + 3] = f1.w;
;         }
;       } else {
; #pragma unroll
;         for (int e = 0; e < 16; ++e) { s0[e] = 0.f; s1[e] = 0.f; }
;       }
;       __builtin_amdgcn_iglp_opt(0);
;       __builtin_amdgcn_s_setprio(1);
; #pragma unroll
;       for (int ks = 0; ks < NKS; ++ks) { s0 = MFMA(kf0[ks], qf[ks], s0); s1 = MFMA(kf1[ks], qf[ks], s1); }
.LBB0_560:
	s_cmp_lt_i32 s2, s0
	s_cselect_b64 s[22:23], -1, 0
	s_cmp_ge_i32 s2, s0
	s_cselect_b64 s[20:21], -1, 0
	s_and_b64 vcc, exec, s[20:21]
	s_cbranch_vccnz .LBB0_562
	s_ashr_i32 s11, s10, 31
	s_lshl_b64 s[24:25], s[10:11], 1
	s_lshl_b64 s[100:101], s[10:11], 7
	s_add_i32 s11, s2, -1
	s_and_b32 s11, s11, 1
	s_sub_i32 s13, s10, 64
	s_cmp_gt_i32 s13, s12
	s_cbranch_scc1 .Lfox_inactive
	s_mul_i32 s13, s11, 0x2400
	v_add_u32_e32 v168, s13, v137
	v_lshl_or_b32 v46, s11, 8, v132
	ds_read_b128 v[98:101], v168 offset:4608
	ds_read_b128 v[102:105], v168
	ds_read_b128 v[106:109], v168 offset:32
	ds_read_b128 v[110:113], v168 offset:4640
	ds_read_b128 v[114:117], v168 offset:64
	ds_read_b128 v[118:121], v168 offset:4672
	ds_read_b128 v[122:125], v168 offset:96
	ds_read_b128 v[50:53], v46 offset:36864
	ds_read_b128 v[54:57], v46 offset:36896
	ds_read_b128 v[34:37], v46 offset:36992
	ds_read_b128 v[38:41], v46 offset:37024
	ds_read_b128 v[58:61], v46 offset:36928
	ds_read_b128 v[42:45], v46 offset:37056
	ds_read_b128 v[62:65], v46 offset:36960
	ds_read_b128 v[46:49], v46 offset:37088
	ds_read_b128 v[164:167], v168 offset:4704
	s_setprio 1
	s_waitcnt lgkmcnt(2)
	v_mfma_f32_32x32x16_bf16 v[50:65], v[102:105], v[66:69], v[50:65]
	ds_read_b128 v[126:129], v168 offset:23040
	ds_read_b128 v[102:105], v168 offset:18528
	s_waitcnt lgkmcnt(3)
	v_mfma_f32_32x32x16_bf16 v[34:49], v[98:101], v[66:69], v[34:49]
	v_lshl_add_u64 v[246:247], v[228:229], 0, s[100:101]
	global_load_dwordx4 v[82:85], v[246:247], off
	ds_read_b128 v[98:101], v168 offset:23136
	v_mfma_f32_32x32x16_bf16 v[50:65], v[106:109], v[70:73], v[50:65]
	v_lshl_add_u64 v[246:247], v[230:231], 0, s[100:101]
	global_load_dwordx4 v[86:89], v[246:247], off
	ds_read_b128 v[106:109], v168 offset:18496
	v_mfma_f32_32x32x16_bf16 v[34:49], v[110:113], v[70:73], v[34:49]
	v_lshl_add_u64 v[246:247], v[142:143], 0, s[24:25]
	global_load_dwordx4 v[90:93], v[246:247], off
	ds_read_b128 v[110:113], v168 offset:23104
	v_mfma_f32_32x32x16_bf16 v[50:65], v[114:117], v[74:77], v[50:65]
	v_lshl_add_u64 v[246:247], v[152:153], 0, s[24:25]
	global_load_dwordx4 v[94:97], v[246:247], off
	ds_read_b128 v[114:117], v168 offset:18464
	v_mfma_f32_32x32x16_bf16 v[34:49], v[118:121], v[74:77], v[34:49]
	v_lshl_add_u64 v[246:247], s[24:25], 1, v[232:233]
	global_load_dword v160, v[246:247], off
	ds_read_b128 v[118:121], v168 offset:23072
	v_mfma_f32_32x32x16_bf16 v[50:65], v[122:125], v[78:81], v[50:65]
	ds_read_b128 v[122:125], v168 offset:18432
	s_waitcnt lgkmcnt(8)
	v_mfma_f32_32x32x16_bf16 v[34:49], v[164:167], v[78:81], v[34:49]
	s_setprio 0
	s_branch .Lfox_qk_done
.Lfox_inactive:
	v_lshl_add_u64 v[34:35], v[228:229], 0, s[100:101]
	v_lshl_add_u64 v[36:37], v[230:231], 0, s[100:101]
	global_load_dwordx4 v[82:85], v[34:35], off
	global_load_dwordx4 v[86:89], v[36:37], off
	v_lshl_add_u64 v[34:35], v[142:143], 0, s[24:25]
	v_lshl_add_u64 v[36:37], v[152:153], 0, s[24:25]
	global_load_dwordx4 v[90:93], v[34:35], off
	global_load_dwordx4 v[94:97], v[36:37], off
	v_lshl_add_u64 v[34:35], s[24:25], 1, v[232:233]
	global_load_dword v160, v[34:35], off
	s_branch .LBB0_568

; template <int DK, int MODE> ...
;     ...
;       const bool need_mask = CAUSAL && (key0 + 63 >= tq0);
;       bf16x8 pf[4];
;       if (MODE != 2) {
;         if (need_mask) {
; #pragma unroll
;           for (int e = 0; e < 16; ++e) {
;             const int key = key0 + 8 * (e >> 2) + 4 * h + (e & 3);
;             if (key > qpos) s0[e] = -1e30f;
;             if (key + 32 > qpos) s1[e] = -1e30f;
;           }
;         }
.Lfox_qk_done:
	s_add_i32 s13, s10, -1
	s_cmp_lt_i32 s13, s1
	s_cbranch_scc1 .LBB0_565
	v_add_u32_e32 v164, s10, v162
	v_subrev_u32_e32 v166, 32, v164
	v_subrev_u32_e32 v165, 64, v164
	v_cmp_le_i32_e32 vcc, v166, v130
	s_nop 4
	v_cndmask_b32_e32 v34, v198, v34, vcc
	v_cmp_lt_i32_e32 vcc, v165, v130
	s_nop 1
	v_cndmask_b32_e32 v51, v198, v51, vcc
	v_cmp_le_i32_e32 vcc, v165, v130
	v_subrev_u32_e32 v165, 31, v164
	s_nop 0
	v_cndmask_b32_e32 v50, v198, v50, vcc
	v_cmp_le_i32_e32 vcc, v165, v130
	v_subrev_u32_e32 v165, 62, v164
	s_nop 0
	v_cndmask_b32_e32 v35, v198, v35, vcc
	v_cmp_le_i32_e32 vcc, v165, v130
	v_subrev_u32_e32 v165, 30, v164
	s_nop 0
	v_cndmask_b32_e32 v52, v198, v52, vcc
	v_cmp_le_i32_e32 vcc, v165, v130
	v_subrev_u32_e32 v165, 61, v164
	s_nop 0
	v_cndmask_b32_e32 v36, v198, v36, vcc
	v_cmp_le_i32_e32 vcc, v165, v130
	v_subrev_u32_e32 v165, 29, v164
	s_nop 0
	v_cndmask_b32_e32 v53, v198, v53, vcc
	v_cmp_le_i32_e32 vcc, v165, v130
	v_subrev_u32_e32 v165, 56, v164
	s_nop 0
	v_cndmask_b32_e32 v37, v198, v37, vcc
	v_cmp_le_i32_e32 vcc, v165, v130
	v_subrev_u32_e32 v165, 24, v164
	s_nop 0
	v_cndmask_b32_e32 v54, v198, v54, vcc
	v_cmp_le_i32_e32 vcc, v165, v130
	v_subrev_u32_e32 v165, 55, v164
	s_nop 0
	v_cndmask_b32_e32 v38, v198, v38, vcc
	v_cmp_le_i32_e32 vcc, v165, v130
	v_subrev_u32_e32 v165, 23, v164
	s_nop 0
	v_cndmask_b32_e32 v55, v198, v55, vcc
	v_cmp_le_i32_e32 vcc, v165, v130
	v_subrev_u32_e32 v165, 54, v164
	s_nop 0
	v_cndmask_b32_e32 v39, v198, v39, vcc
	v_cmp_le_i32_e32 vcc, v165, v130
	v_subrev_u32_e32 v165, 22, v164
	s_nop 0
	v_cndmask_b32_e32 v56, v198, v56, vcc
	v_cmp_le_i32_e32 vcc, v165, v130
	v_subrev_u32_e32 v165, 53, v164
	s_nop 0
	v_cndmask_b32_e32 v40, v198, v40, vcc
	v_cmp_le_i32_e32 vcc, v165, v130
	v_subrev_u32_e32 v165, 21, v164
	s_nop 0
	v_cndmask_b32_e32 v57, v198, v57, vcc
	v_cmp_le_i32_e32 vcc, v165, v130
	v_subrev_u32_e32 v165, 48, v164
	s_nop 0
	v_cndmask_b32_e32 v41, v198, v41, vcc
	v_cmp_le_i32_e32 vcc, v165, v130
	v_add_u32_e32 v165, -16, v164
	s_nop 0
	v_cndmask_b32_e32 v58, v198, v58, vcc
	v_cmp_le_i32_e32 vcc, v165, v130
	v_subrev_u32_e32 v165, 47, v164
	s_nop 0
	v_cndmask_b32_e32 v42, v198, v42, vcc
	v_cmp_le_i32_e32 vcc, v165, v130
	v_add_u32_e32 v165, -15, v164
	s_nop 0
	v_cndmask_b32_e32 v59, v198, v59, vcc
	v_cmp_le_i32_e32 vcc, v165, v130
	v_subrev_u32_e32 v165, 46, v164
	s_nop 0
	v_cndmask_b32_e32 v43, v198, v43, vcc
	v_cmp_le_i32_e32 vcc, v165, v130
	v_add_u32_e32 v165, -14, v164
	s_nop 0
	v_cndmask_b32_e32 v60, v198, v60, vcc
	v_cmp_le_i32_e32 vcc, v165, v130
	v_subrev_u32_e32 v165, 45, v164
	s_nop 0
	v_cndmask_b32_e32 v44, v198, v44, vcc
	v_cmp_le_i32_e32 vcc, v165, v130
	v_add_u32_e32 v165, -13, v164
	s_nop 0
	v_cndmask_b32_e32 v61, v198, v61, vcc
	v_cmp_le_i32_e32 vcc, v165, v130
	v_subrev_u32_e32 v165, 40, v164
	s_nop 0
	v_cndmask_b32_e32 v45, v198, v45, vcc
	v_cmp_le_i32_e32 vcc, v165, v130
	v_add_u32_e32 v165, -8, v164
	s_nop 0
	v_cndmask_b32_e32 v62, v198, v62, vcc
	v_cmp_le_i32_e32 vcc, v165, v130
	v_subrev_u32_e32 v165, 39, v164
	s_nop 0
	v_cndmask_b32_e32 v46, v198, v46, vcc
	v_cmp_le_i32_e32 vcc, v165, v130
	v_add_u32_e32 v165, -7, v164
	s_nop 0
	v_cndmask_b32_e32 v63, v198, v63, vcc
	v_cmp_le_i32_e32 vcc, v165, v130
	v_subrev_u32_e32 v165, 38, v164
	s_nop 0
	v_cndmask_b32_e32 v47, v198, v47, vcc
	v_cmp_le_i32_e32 vcc, v165, v130
	v_add_u32_e32 v165, -6, v164
	s_nop 0
	v_cndmask_b32_e32 v64, v198, v64, vcc
	v_cmp_le_i32_e32 vcc, v165, v130
	v_subrev_u32_e32 v165, 37, v164
	v_add_u32_e32 v164, -5, v164
	v_cndmask_b32_e32 v48, v198, v48, vcc
	v_cmp_le_i32_e32 vcc, v165, v130
	s_nop 1
	v_cndmask_b32_e32 v65, v198, v65, vcc
	v_cmp_le_i32_e32 vcc, v164, v130
	s_nop 1
	v_cndmask_b32_e32 v49, v198, v49, vcc
